# v16 + final RMSNorm output pass: row-invariant g_final slices hoisted into 64 VGPRs before the row loop; per-row load-wait(0)-store ladder (16 drains per row) removed
# speedup vs baseline: 1.0003x; 1.0003x over previous
.LBB0_1526:
	s_waitcnt vmcnt(0) lgkmcnt(0)
	v_lshlrev_b32_e32 v4, 1, v28
	v_readlane_b32 s8, v252, 6
	v_ashrrev_i32_e32 v5, 31, v4
	v_readlane_b32 s14, v252, 12
	v_readlane_b32 s15, v252, 13
	s_mov_b64 s[0:1], 0x1000
	v_ashrrev_i32_e32 v29, 31, v28
	v_lshl_add_u64 v[6:7], v[4:5], 4, s[14:15]
	v_lshl_add_u64 v[8:9], v[6:7], 0, s[0:1]
	s_mov_b64 s[0:1], 0x1010
	v_lshl_add_u64 v[10:11], v[6:7], 0, s[0:1]
	s_mov_b64 s[0:1], 0x1800
	v_lshl_add_u64 v[12:13], v[6:7], 0, s[0:1]
	s_mov_b64 s[0:1], 0x1810
	v_lshl_add_u64 v[14:15], v[6:7], 0, s[0:1]
	s_mov_b64 s[0:1], 0x2000
	v_lshl_add_u64 v[16:17], v[6:7], 0, s[0:1]
	s_mov_b64 s[0:1], 0x2010
	v_lshl_add_u64 v[18:19], v[6:7], 0, s[0:1]
	s_mov_b64 s[0:1], 0x2800
	v_lshl_add_u64 v[20:21], v[6:7], 0, s[0:1]
	s_mov_b64 s[0:1], 0x2810
	v_lshl_add_u64 v[22:23], v[6:7], 0, s[0:1]
	s_mov_b64 s[0:1], 0x3000
	v_lshl_add_u64 v[24:25], v[6:7], 0, s[0:1]
	s_mov_b64 s[0:1], 0x3010
	v_lshl_add_u64 v[26:27], v[6:7], 0, s[0:1]
	s_mov_b64 s[0:1], 0x3800
	v_lshl_add_u64 v[30:31], v[6:7], 0, s[0:1]
	s_mov_b64 s[0:1], 0x3810
	v_lshl_add_u64 v[32:33], v[6:7], 0, s[0:1]
	v_readlane_b32 s0, v252, 16
	v_lshl_add_u64 v[28:29], v[28:29], 4, s[6:7]
	s_mov_b32 s4, s0
	v_readlane_b32 s9, v252, 7
	v_readlane_b32 s10, v252, 8
	v_readlane_b32 s11, v252, 9
	v_readlane_b32 s12, v252, 10
	v_readlane_b32 s13, v252, 11
	global_load_dwordx4 v[148:151], v[6:7], off
	global_load_dwordx4 v[152:155], v[6:7], off offset:16
	global_load_dwordx4 v[156:159], v[6:7], off offset:2048
	global_load_dwordx4 v[160:163], v[6:7], off offset:2064
	global_load_dwordx4 v[164:167], v[8:9], off
	global_load_dwordx4 v[168:171], v[10:11], off
	global_load_dwordx4 v[172:175], v[12:13], off
	global_load_dwordx4 v[176:179], v[14:15], off
	global_load_dwordx4 v[180:183], v[16:17], off
	global_load_dwordx4 v[188:191], v[18:19], off
	global_load_dwordx4 v[192:195], v[20:21], off
	global_load_dwordx4 v[196:199], v[22:23], off
	global_load_dwordx4 v[200:203], v[24:25], off
	global_load_dwordx4 v[224:227], v[26:27], off
	global_load_dwordx4 v[228:231], v[30:31], off
	global_load_dwordx4 v[232:235], v[32:33], off
	s_waitcnt vmcnt(0)
	s_branch .LBB0_1528

.LBB0_1528:
	s_mul_hi_i32 s0, s4, 0x7f807f81
	s_lshr_b32 s1, s0, 31
	s_ashr_i32 s0, s0, 11
	s_add_i32 s6, s0, s1
	s_mul_i32 s0, s6, 0xffffeff0
	s_add_i32 s2, s4, s0
	s_cmp_lt_i32 s2, 16
	s_cbranch_scc1 .LBB0_1527
	s_ashr_i32 s5, s4, 31
	s_lshl_b64 s[0:1], s[4:5], 13
	v_lshl_add_u64 v[38:39], v[28:29], 0, s[0:1]
	global_load_dwordx4 v[34:37], v[38:39], off offset:3072
	global_load_dwordx4 v[46:49], v[38:39], off
	global_load_dwordx4 v[50:53], v[38:39], off offset:1024
	global_load_dwordx4 v[54:57], v[38:39], off offset:2048
	s_movk_i32 s5, 0x1000
	v_add_co_u32_e32 v38, vcc, s5, v38
	s_ashr_i32 s7, s6, 31
	s_nop 0
	v_addc_co_u32_e32 v39, vcc, 0, v39, vcc
	global_load_dwordx4 v[102:105], v[38:39], off offset:3072
	global_load_dwordx4 v[62:65], v[38:39], off
	global_load_dwordx4 v[106:109], v[38:39], off offset:2048
	global_load_dwordx4 v[110:113], v[38:39], off offset:1024
	s_add_i32 s88, s2, -16
	v_readlane_b32 s8, v252, 2
	v_readlane_b32 s9, v252, 3
	v_readlane_b32 s10, v252, 4
	v_readlane_b32 s11, v252, 5
	s_waitcnt vmcnt(7)
	v_lshlrev_b32_e32 v44, 16, v35
	v_and_b32_e32 v45, 0xffff0000, v35
	s_waitcnt vmcnt(6)
	v_and_b32_e32 v99, 0xffff0000, v47
	v_and_b32_e32 v97, 0xffff0000, v46
	v_and_b32_e32 v96, 0xffff0000, v48
	s_waitcnt vmcnt(4)
	v_and_b32_e32 v69, 0xffff0000, v54
	v_and_b32_e32 v73, 0xffff0000, v55
	v_lshlrev_b32_e32 v61, 16, v34
	v_and_b32_e32 v59, 0xffff0000, v34
	v_pk_mov_b32 v[34:35], v[56:57], v[36:37] op_sel:[1,0]
	v_lshlrev_b32_e32 v43, 16, v37
	v_and_b32_e32 v41, 0xffff0000, v37
	v_lshlrev_b32_e32 v98, 16, v47
	v_lshlrev_b32_e32 v95, 16, v46
	v_lshlrev_b32_e32 v94, 16, v48
	v_and_b32_e32 v93, 0xffff0000, v51
	v_and_b32_e32 v92, 0xffff0000, v50
	v_lshlrev_b32_e32 v68, 16, v54
	v_lshlrev_b32_e32 v72, 16, v55
	v_lshlrev_b32_e32 v60, 16, v56
	v_and_b32_e32 v58, 0xffff0000, v56
	v_lshlrev_b32_e32 v55, 16, v36
	v_lshlrev_b32_e32 v54, 16, v57
	v_mul_f32_e32 v2, v99, v99
	v_pk_mul_f32 v[46:47], v[96:97], v[96:97]
	v_and_b32_e32 v57, 0xffff0000, v35
	v_and_b32_e32 v56, 0xffff0000, v34
	v_mul_f32_e32 v34, v69, v69
	v_mul_f32_e32 v36, v73, v73
	s_waitcnt vmcnt(3)
	v_lshlrev_b32_e32 v37, 16, v105
	v_and_b32_e32 v35, 0xffff0000, v105
	v_lshlrev_b32_e32 v100, 16, v49
	v_and_b32_e32 v101, 0xffff0000, v49
	v_lshlrev_b32_e32 v89, 16, v51
	v_lshlrev_b32_e32 v88, 16, v50
	v_and_b32_e32 v85, 0xffff0000, v53
	v_and_b32_e32 v84, 0xffff0000, v52
	v_pk_mul_f32 v[48:49], v[92:93], v[92:93]
	v_mul_f32_e32 v42, v44, v44
	v_mul_f32_e32 v66, v45, v45
	v_pk_fma_f32 v[70:71], v[98:99], v[98:99], v[2:3] op_sel_hi:[1,1,0]
	v_pk_fma_f32 v[46:47], v[94:95], v[94:95], v[46:47]
	v_pk_fma_f32 v[74:75], v[68:69], v[68:69], v[34:35] op_sel_hi:[1,1,0]
	v_pk_fma_f32 v[76:77], v[72:73], v[72:73], v[36:37] op_sel_hi:[1,1,0]
	v_lshlrev_b32_e32 v81, 16, v53
	v_lshlrev_b32_e32 v80, 16, v52
	v_pk_mul_f32 v[50:51], v[84:85], v[84:85]
	v_pk_mul_f32 v[52:53], v[58:59], v[58:59]
	v_mul_f32_e32 v40, v101, v101
	v_pk_fma_f32 v[48:49], v[88:89], v[88:89], v[48:49]
	v_pk_add_f32 v[70:71], v[46:47], v[70:71] op_sel:[1,0] op_sel_hi:[0,1]
	v_mov_b32_e32 v75, v42
	v_mov_b32_e32 v77, v66
	v_pk_fma_f32 v[50:51], v[80:81], v[80:81], v[50:51]
	v_pk_fma_f32 v[52:53], v[60:61], v[60:61], v[52:53]
	v_pk_mul_f32 v[78:79], v[56:57], v[56:57]
	v_pk_fma_f32 v[82:83], v[100:101], v[100:101], v[40:41] op_sel_hi:[1,1,0]
	v_pk_add_f32 v[48:49], v[48:49], v[48:49] op_sel:[0,1] op_sel_hi:[1,0]
	v_pk_add_f32 v[46:47], v[46:47], v[70:71]
	v_pk_add_f32 v[70:71], v[74:75], v[76:77]
	v_mov_b32_e32 v67, v43
	v_pk_fma_f32 v[78:79], v[54:55], v[54:55], v[78:79]
	v_mov_b32_e32 v42, v82
	v_pk_add_f32 v[48:49], v[50:51], v[48:49]
	v_pk_add_f32 v[52:53], v[52:53], v[70:71]
	v_mov_b32_e32 v66, v46
	v_mul_f32_e32 v86, v41, v41
	v_pk_add_f32 v[46:47], v[82:83], v[46:47]
	v_pk_add_f32 v[48:49], v[50:51], v[48:49] op_sel:[1,0] op_sel_hi:[0,1]
	v_pk_add_f32 v[50:51], v[78:79], v[52:53]
	v_pk_mul_f32 v[52:53], v[42:43], v[66:67]
	v_mov_b32_e32 v49, v86
	v_mov_b32_e32 v47, v53
	v_pk_add_f32 v[46:47], v[46:47], v[48:49]
	s_waitcnt vmcnt(2)
	v_and_b32_e32 v91, 0xffff0000, v63
	v_and_b32_e32 v90, 0xffff0000, v62
	v_pk_add_f32 v[114:115], v[46:47], v[50:51]
	v_lshlrev_b32_e32 v87, 16, v63
	v_lshlrev_b32_e32 v86, 16, v62
	v_pk_mul_f32 v[46:47], v[90:91], v[90:91]
	v_and_b32_e32 v83, 0xffff0000, v65
	v_and_b32_e32 v82, 0xffff0000, v64
	v_pk_fma_f32 v[46:47], v[86:87], v[86:87], v[46:47]
	v_lshlrev_b32_e32 v79, 16, v65
	v_lshlrev_b32_e32 v78, 16, v64
	v_pk_mul_f32 v[48:49], v[82:83], v[82:83]
	v_pk_add_f32 v[46:47], v[46:47], v[46:47] op_sel:[0,1] op_sel_hi:[1,0]
	v_pk_fma_f32 v[48:49], v[78:79], v[78:79], v[48:49]
	s_waitcnt vmcnt(0)
	v_and_b32_e32 v77, 0xffff0000, v111
	v_pk_add_f32 v[46:47], v[48:49], v[46:47]
	v_and_b32_e32 v76, 0xffff0000, v110
	v_pk_add_f32 v[116:117], v[48:49], v[46:47] op_sel:[1,0] op_sel_hi:[0,1]
	v_lshlrev_b32_e32 v75, 16, v111
	v_lshlrev_b32_e32 v74, 16, v110
	v_pk_mul_f32 v[46:47], v[76:77], v[76:77]
	v_and_b32_e32 v71, 0xffff0000, v113
	v_and_b32_e32 v70, 0xffff0000, v112
	v_pk_fma_f32 v[46:47], v[74:75], v[74:75], v[46:47]
	v_lshlrev_b32_e32 v67, 16, v113
	v_lshlrev_b32_e32 v66, 16, v112
	v_pk_mul_f32 v[48:49], v[70:71], v[70:71]
	v_and_b32_e32 v63, 0xffff0000, v106
	v_pk_add_f32 v[46:47], v[46:47], v[46:47] op_sel:[0,1] op_sel_hi:[1,0]
	v_pk_fma_f32 v[110:111], v[66:67], v[66:67], v[48:49]
	v_lshlrev_b32_e32 v62, 16, v106
	v_and_b32_e32 v65, 0xffff0000, v107
	v_mul_f32_e32 v2, v63, v63
	v_lshlrev_b32_e32 v38, 16, v103
	v_and_b32_e32 v39, 0xffff0000, v103
	v_pk_add_f32 v[112:113], v[110:111], v[46:47]
	v_lshlrev_b32_e32 v64, 16, v107
	v_pk_mov_b32 v[46:47], v[108:109], v[104:105] op_sel:[1,0]
	v_lshlrev_b32_e32 v49, 16, v104
	v_pk_fma_f32 v[104:105], v[62:63], v[62:63], v[2:3] op_sel_hi:[1,1,0]
	v_mul_f32_e32 v2, v65, v65
	v_mul_f32_e32 v34, v38, v38
	v_mul_f32_e32 v36, v39, v39
	v_and_b32_e32 v51, 0xffff0000, v102
	v_and_b32_e32 v50, 0xffff0000, v108
	v_pk_fma_f32 v[106:107], v[64:65], v[64:65], v[2:3] op_sel_hi:[1,1,0]
	v_lshlrev_b32_e32 v53, 16, v102
	v_lshlrev_b32_e32 v52, 16, v108
	v_pk_mul_f32 v[102:103], v[50:51], v[50:51]
	v_mov_b32_e32 v105, v34
	v_mov_b32_e32 v107, v36
	v_and_b32_e32 v47, 0xffff0000, v47
	v_and_b32_e32 v46, 0xffff0000, v46
	v_pk_fma_f32 v[102:103], v[52:53], v[52:53], v[102:103]
	v_pk_add_f32 v[104:105], v[104:105], v[106:107]
	v_lshlrev_b32_e32 v48, 16, v109
	v_pk_add_f32 v[102:103], v[102:103], v[104:105]
	v_pk_mul_f32 v[104:105], v[46:47], v[46:47]
	v_mov_b32_e32 v106, v116
	v_pk_fma_f32 v[104:105], v[48:49], v[48:49], v[104:105]
	v_mov_b32_e32 v107, v37
	v_pk_add_f32 v[102:103], v[104:105], v[102:103]
	v_pk_add_f32 v[104:105], v[114:115], v[114:115] op_sel:[0,1] op_sel_hi:[1,0]
	v_mul_f32_e32 v40, v35, v35
	v_mov_b32_e32 v36, v104
	v_pk_add_f32 v[104:105], v[104:105], v[116:117]
	v_pk_mul_f32 v[106:107], v[36:37], v[106:107]
	v_and_b32_e32 v34, 64, v211
	v_mov_b32_e32 v105, v107
	v_pk_add_f32 v[106:107], v[110:111], v[112:113] op_sel:[1,0] op_sel_hi:[0,1]
	v_mov_b32_e32 v107, v40
	v_add_u32_e32 v34, 64, v34
	v_xor_b32_e32 v36, 1, v211
	v_pk_add_f32 v[104:105], v[104:105], v[106:107]
	v_cmp_lt_i32_e32 vcc, v36, v34
	v_pk_add_f32 v[102:103], v[104:105], v[102:103]
	s_nop 1
	v_mov_b64_e32 v[104:105], v[148:149]
	v_mov_b64_e32 v[106:107], v[150:151]
	v_cndmask_b32_e32 v36, v211, v36, vcc
	v_add_f32_e32 v2, v102, v103
	v_lshlrev_b32_e32 v36, 2, v36
	ds_bpermute_b32 v36, v36, v2
	v_mov_b32_e32 v108, v95
	v_mov_b32_e32 v109, v97
	v_mov_b32_e32 v95, v96
	s_waitcnt lgkmcnt(0)
	v_add_f32_e32 v2, v2, v36
	v_xor_b32_e32 v36, 2, v211
	v_cmp_lt_i32_e32 vcc, v36, v34
	s_nop 1
	v_cndmask_b32_e32 v36, v211, v36, vcc
	v_lshlrev_b32_e32 v36, 2, v36
	ds_bpermute_b32 v36, v36, v2
	s_waitcnt lgkmcnt(0)
	v_add_f32_e32 v2, v2, v36
	v_xor_b32_e32 v36, 4, v211
	v_cmp_lt_i32_e32 vcc, v36, v34
	s_nop 1
	v_cndmask_b32_e32 v36, v211, v36, vcc
	v_lshlrev_b32_e32 v36, 2, v36
	ds_bpermute_b32 v36, v36, v2
	s_waitcnt lgkmcnt(0)
	v_add_f32_e32 v2, v2, v36
	v_xor_b32_e32 v36, 8, v211
	v_cmp_lt_i32_e32 vcc, v36, v34
	s_nop 1
	v_cndmask_b32_e32 v36, v211, v36, vcc
	v_lshlrev_b32_e32 v36, 2, v36
	ds_bpermute_b32 v36, v36, v2
	s_waitcnt lgkmcnt(0)
	v_add_f32_e32 v2, v2, v36
	v_xor_b32_e32 v36, 16, v211
	v_cmp_lt_i32_e32 vcc, v36, v34
	s_nop 1
	v_cndmask_b32_e32 v36, v211, v36, vcc
	v_lshlrev_b32_e32 v36, 2, v36
	ds_bpermute_b32 v36, v36, v2
	s_waitcnt lgkmcnt(0)
	v_add_f32_e32 v2, v2, v36
	v_xor_b32_e32 v36, 32, v211
	v_cmp_lt_i32_e32 vcc, v36, v34
	s_nop 1
	v_cndmask_b32_e32 v34, v211, v36, vcc
	v_lshlrev_b32_e32 v34, 2, v34
	ds_bpermute_b32 v34, v34, v2
	s_waitcnt lgkmcnt(0)
	v_add_f32_e32 v2, v2, v34
	v_fmamk_f32 v2, v2, 0x39800000, v209
	v_mul_f32_e32 v34, 0x4f800000, v2
	v_cmp_gt_f32_e32 vcc, s20, v2
	s_nop 1
	v_cndmask_b32_e32 v2, v2, v34, vcc
	v_sqrt_f32_e32 v34, v2
	s_nop 0
	v_add_u32_e32 v36, -1, v34
	v_fma_f32 v40, -v36, v34, v2
	v_cmp_ge_f32_e64 s[0:1], 0, v40
	v_add_u32_e32 v40, 1, v34
	s_nop 0
	v_cndmask_b32_e64 v36, v34, v36, s[0:1]
	v_fma_f32 v34, -v40, v34, v2
	v_cmp_lt_f32_e64 s[0:1], 0, v34
	s_nop 1
	v_cndmask_b32_e64 v34, v36, v40, s[0:1]
	v_mul_f32_e32 v36, 0x37800000, v34
	v_cndmask_b32_e32 v34, v34, v36, vcc
	v_cmp_class_f32_e32 vcc, v2, v210
	s_nop 1
	v_cndmask_b32_e32 v2, v34, v2, vcc
	v_div_scale_f32 v34, s[0:1], v2, v2, 1.0
	v_rcp_f32_e32 v36, v34
	s_lshl_b64 s[0:1], s[6:7], 26
	s_add_u32 s2, s8, s0
	s_addc_u32 s3, s9, s1
	v_fma_f32 v40, -v34, v36, 1.0
	v_fmac_f32_e32 v36, v40, v36
	v_div_scale_f32 v40, vcc, 1.0, v2, 1.0
	v_mul_f32_e32 v42, v40, v36
	v_fma_f32 v102, -v34, v42, v40
	v_fmac_f32_e32 v42, v102, v36
	v_fma_f32 v34, -v34, v42, v40
	v_div_fmas_f32 v34, v34, v36, v42
	s_lshl_b64 s[0:1], s[88:89], 14
	v_div_fixup_f32 v2, v34, v2, 1.0
	s_add_u32 s0, s2, s0
	s_addc_u32 s1, s3, s1
	v_pk_mul_f32 v[108:109], v[2:3], v[108:109] op_sel_hi:[0,1]
	v_pk_mul_f32 v[98:99], v[2:3], v[98:99] op_sel_hi:[0,1]
	v_lshl_add_u64 v[102:103], v[4:5], 4, s[0:1]
	s_nop 0
	v_pk_mul_f32 v[106:107], v[106:107], v[98:99]
	v_pk_mul_f32 v[104:105], v[104:105], v[108:109]
	global_store_dwordx4 v[102:103], v[104:107], off
	s_nop 1
	v_mov_b64_e32 v[104:105], v[152:153]
	v_mov_b64_e32 v[106:107], v[154:155]
	v_pk_mul_f32 v[98:99], v[2:3], v[100:101] op_sel_hi:[0,1]
	v_pk_mul_f32 v[94:95], v[2:3], v[94:95] op_sel_hi:[0,1]
	s_movk_i32 s0, 0x2000
	v_pk_mul_f32 v[72:73], v[2:3], v[72:73] op_sel_hi:[0,1]
	v_pk_mul_f32 v[68:69], v[2:3], v[68:69] op_sel_hi:[0,1]
	v_pk_mul_f32 v[44:45], v[2:3], v[44:45] op_sel_hi:[0,1]
	v_mov_b32_e32 v40, v43
	v_pk_mul_f32 v[42:43], v[2:3], v[40:41] op_sel_hi:[0,1]
	v_mov_b32_e32 v34, v37
	v_pk_mul_f32 v[36:37], v[2:3], v[34:35] op_sel_hi:[0,1]
	s_nop 0
	v_pk_mul_f32 v[94:95], v[104:105], v[94:95]
	v_pk_mul_f32 v[96:97], v[106:107], v[98:99]
	global_store_dwordx4 v[102:103], v[94:97], off offset:16
	s_nop 1
	v_mov_b64_e32 v[94:95], v[156:157]
	v_mov_b64_e32 v[96:97], v[158:159]
	v_mov_b32_e32 v98, v89
	v_mov_b32_e32 v99, v93
	v_mov_b32_e32 v89, v92
	v_pk_mul_f32 v[98:99], v[2:3], v[98:99] op_sel_hi:[0,1]
	v_pk_mul_f32 v[88:89], v[2:3], v[88:89] op_sel_hi:[0,1]
	s_nop 0
	v_pk_mul_f32 v[92:93], v[94:95], v[88:89]
	v_pk_mul_f32 v[94:95], v[96:97], v[98:99]
	global_store_dwordx4 v[102:103], v[92:95], off offset:2048
	s_nop 1
	v_mov_b64_e32 v[92:93], v[160:161]
	v_mov_b64_e32 v[94:95], v[162:163]
	v_mov_b32_e32 v88, v81
	v_mov_b32_e32 v89, v85
	v_mov_b32_e32 v81, v84
	v_pk_mul_f32 v[84:85], v[2:3], v[88:89] op_sel_hi:[0,1]
	v_pk_mul_f32 v[80:81], v[2:3], v[80:81] op_sel_hi:[0,1]
	s_nop 0
	v_pk_mul_f32 v[92:93], v[92:93], v[80:81]
	v_pk_mul_f32 v[94:95], v[94:95], v[84:85]
	global_store_dwordx4 v[102:103], v[92:95], off offset:2064
	s_nop 1
	v_mov_b64_e32 v[92:93], v[164:165]
	v_mov_b64_e32 v[94:95], v[166:167]
	v_add_co_u32_e32 v80, vcc, s0, v102
	v_mov_b32_e32 v84, v60
	s_nop 0
	v_addc_co_u32_e32 v81, vcc, 0, v103, vcc
	v_mov_b32_e32 v85, v58
	v_pk_mul_f32 v[84:85], v[2:3], v[84:85] op_sel_hi:[0,1]
	v_mov_b32_e32 v58, v61
	v_pk_mul_f32 v[58:59], v[2:3], v[58:59] op_sel_hi:[0,1]
	s_movk_i32 s0, 0x3000
	s_nop 0
	v_pk_mul_f32 v[92:93], v[92:93], v[68:69]
	v_pk_mul_f32 v[94:95], v[94:95], v[72:73]
	global_store_dwordx4 v[80:81], v[92:95], off offset:-4096
	s_nop 1
	v_mov_b64_e32 v[92:93], v[168:169]
	v_mov_b64_e32 v[94:95], v[170:171]
	v_mov_b32_e32 v72, v54
	v_mov_b32_e32 v73, v56
	v_add_co_u32_e32 v68, vcc, s5, v102
	v_pk_mul_f32 v[72:73], v[2:3], v[72:73] op_sel_hi:[0,1]
	s_nop 0
	v_addc_co_u32_e32 v69, vcc, 0, v103, vcc
	v_mov_b32_e32 v56, v55
	v_pk_mul_f32 v[40:41], v[2:3], v[56:57] op_sel_hi:[0,1]
	v_pk_mul_f32 v[56:57], v[2:3], v[62:63] op_sel_hi:[0,1]
	s_nop 0
	v_pk_mul_f32 v[92:93], v[92:93], v[84:85]
	v_pk_mul_f32 v[94:95], v[94:95], v[72:73]
	global_store_dwordx4 v[68:69], v[92:95], off offset:16
	s_nop 1
	v_mov_b64_e32 v[92:93], v[172:173]
	v_mov_b64_e32 v[94:95], v[174:175]
	s_nop 0
	v_pk_mul_f32 v[58:59], v[92:93], v[58:59]
	v_pk_mul_f32 v[60:61], v[94:95], v[44:45]
	global_store_dwordx4 v[68:69], v[58:61], off offset:2048
	s_nop 1
	v_mov_b64_e32 v[58:59], v[176:177]
	v_mov_b64_e32 v[60:61], v[178:179]
	v_mov_b32_e32 v44, v87
	v_mov_b32_e32 v45, v91
	v_mov_b32_e32 v87, v90
	v_pk_mul_f32 v[44:45], v[2:3], v[44:45] op_sel_hi:[0,1]
	v_pk_mul_f32 v[54:55], v[2:3], v[86:87] op_sel_hi:[0,1]
	s_nop 0
	v_pk_mul_f32 v[40:41], v[40:41], v[58:59]
	v_pk_mul_f32 v[42:43], v[42:43], v[60:61]
	global_store_dwordx4 v[68:69], v[40:43], off offset:2064
	s_nop 1
	v_mov_b64_e32 v[40:41], v[180:181]
	v_mov_b64_e32 v[42:43], v[182:183]
	s_nop 0
	v_pk_mul_f32 v[40:41], v[54:55], v[40:41]
	v_pk_mul_f32 v[42:43], v[44:45], v[42:43]
	global_store_dwordx4 v[80:81], v[40:43], off
	s_nop 1
	v_mov_b64_e32 v[40:41], v[188:189]
	v_mov_b64_e32 v[42:43], v[190:191]
	v_mov_b32_e32 v44, v79
	v_mov_b32_e32 v45, v83
	v_mov_b32_e32 v79, v82
	v_pk_mul_f32 v[44:45], v[2:3], v[44:45] op_sel_hi:[0,1]
	v_pk_mul_f32 v[54:55], v[2:3], v[78:79] op_sel_hi:[0,1]
	s_nop 0
	v_pk_mul_f32 v[40:41], v[54:55], v[40:41]
	v_pk_mul_f32 v[42:43], v[44:45], v[42:43]
	global_store_dwordx4 v[80:81], v[40:43], off offset:16
	s_nop 1
	v_mov_b64_e32 v[40:41], v[192:193]
	v_mov_b64_e32 v[42:43], v[194:195]
	v_mov_b32_e32 v44, v75
	v_mov_b32_e32 v45, v77
	v_mov_b32_e32 v75, v76
	v_pk_mul_f32 v[44:45], v[2:3], v[44:45] op_sel_hi:[0,1]
	v_pk_mul_f32 v[54:55], v[2:3], v[74:75] op_sel_hi:[0,1]
	s_nop 0
	v_pk_mul_f32 v[40:41], v[54:55], v[40:41]
	v_pk_mul_f32 v[42:43], v[44:45], v[42:43]
	global_store_dwordx4 v[80:81], v[40:43], off offset:2048
	s_nop 1
	v_mov_b64_e32 v[40:41], v[196:197]
	v_mov_b64_e32 v[42:43], v[198:199]
	v_mov_b32_e32 v44, v67
	v_mov_b32_e32 v45, v71
	v_mov_b32_e32 v67, v70
	v_pk_mul_f32 v[44:45], v[2:3], v[44:45] op_sel_hi:[0,1]
	v_pk_mul_f32 v[54:55], v[2:3], v[66:67] op_sel_hi:[0,1]
	s_nop 0
	v_pk_mul_f32 v[40:41], v[54:55], v[40:41]
	v_pk_mul_f32 v[42:43], v[44:45], v[42:43]
	global_store_dwordx4 v[80:81], v[40:43], off offset:2064
	s_nop 1
	v_mov_b64_e32 v[40:41], v[200:201]
	v_mov_b64_e32 v[42:43], v[202:203]
	v_add_co_u32_e32 v44, vcc, s0, v102
	v_pk_mul_f32 v[54:55], v[2:3], v[64:65] op_sel_hi:[0,1]
	s_nop 0
	v_addc_co_u32_e32 v45, vcc, 0, v103, vcc
	s_nop 0
	v_pk_mul_f32 v[40:41], v[56:57], v[40:41]
	v_pk_mul_f32 v[42:43], v[54:55], v[42:43]
	global_store_dwordx4 v[44:45], v[40:43], off
	s_nop 1
	v_mov_b64_e32 v[40:41], v[224:225]
	v_mov_b64_e32 v[42:43], v[226:227]
	v_mov_b32_e32 v54, v48
	v_mov_b32_e32 v56, v52
	v_mov_b32_e32 v57, v50
	v_mov_b32_e32 v55, v46
	v_pk_mul_f32 v[54:55], v[2:3], v[54:55] op_sel_hi:[0,1]
	v_pk_mul_f32 v[56:57], v[2:3], v[56:57] op_sel_hi:[0,1]
	v_mov_b32_e32 v50, v53
	v_pk_mul_f32 v[52:53], v[2:3], v[38:39] op_sel_hi:[0,1]
	v_pk_mul_f32 v[38:39], v[2:3], v[50:51] op_sel_hi:[0,1]
	v_mov_b32_e32 v46, v49
	v_pk_mul_f32 v[34:35], v[2:3], v[46:47] op_sel_hi:[0,1]
	s_nop 0
	v_pk_mul_f32 v[40:41], v[56:57], v[40:41]
	v_pk_mul_f32 v[42:43], v[54:55], v[42:43]
	global_store_dwordx4 v[44:45], v[40:43], off offset:16
	s_nop 1
	v_mov_b64_e32 v[40:41], v[228:229]
	v_mov_b64_e32 v[42:43], v[230:231]
	s_nop 0
	v_pk_mul_f32 v[38:39], v[38:39], v[40:41]
	v_pk_mul_f32 v[40:41], v[52:53], v[42:43]
	global_store_dwordx4 v[44:45], v[38:41], off offset:2048
	s_nop 1
	v_mov_b64_e32 v[38:39], v[232:233]
	v_mov_b64_e32 v[40:41], v[234:235]
	s_nop 0
	v_pk_mul_f32 v[34:35], v[34:35], v[38:39]
	v_pk_mul_f32 v[36:37], v[36:37], v[40:41]
	global_store_dwordx4 v[44:45], v[34:37], off offset:2064
	s_branch .LBB0_1527
